# P3 pipelined epilogue plus 10us start stagger of CU groups 1-3 in P3 (they have one tile less)
# baseline (speedup 1.0000x reference)
; #define SEAM(k) do { if (IN(k) && IN((k) + 1)) { if (a.ph_hi > 4096) cg::this_grid().sync(); else xcd_barrier(xbar); } } while (0)
;     __host__ __device__ bool next(int i, Unit& u) const {
;         const long L = (long)i * G + c; if (L >= nwg) return false;
;         int wgid = (int)L; { const int q = nwg / NXCD, r = nwg % NXCD, xcd = wgid % NXCD, off = wgid / NXCD; wgid = (xcd < r ? xcd * (q + 1) : r * (q + 1) + (xcd - r) * q) + off; }
;         const int nig = WGM * nN, gid = wgid / nig, fm = gid * WGM, gsz = (nM - fm) < WGM ? (nM - fm) : WGM;
;         u.pm = fm + ((wgid % nig) % gsz); u.pn = (wgid % nig) / gsz; return true;
; __global__ void __launch_bounds__(512, 2) fwd_kernel(Args a) {
;     ...
;     if (IN(3)) { pg8::Gemm g{ZH, (const bf16_t*)(ws + WS_W1B), MALL, D, DFF}; pg8::StaticOrder S; S.init(MALL, D, G, (int)blockIdx.x); typedef EpiResid<2, true, true, 4> EpiT; EpiT E{a.in[I_X], a.in[I_CTX], a.out, X1C, mod, XN, a.in[I_N2G], (float*)(ws + WS_RS2)};
;         pg8::gemm_phase<EpiT, pg8::StaticOrder, true, true>(ldsg, g, S, E); } SEAM(3);
.LBB0_363:
	s_lshr_b32 s100, s2, 6
	s_and_b32 s100, s100, 3
	s_mul_i32 s100, s100, 1000
	s_memrealtime s[98:99]
	s_waitcnt lgkmcnt(0)
	s_add_u32 s100, s100, s98
.Lstag_p3:
	s_sleep 8
	s_memrealtime s[98:99]
	s_waitcnt lgkmcnt(0)
	s_sub_u32 s101, s100, s98
	s_cmp_gt_i32 s101, 0
	s_cbranch_scc1 .Lstag_p3
	s_cmp_lt_i32 s90, 4
	s_cselect_b64 s[0:1], -1, 0
	s_and_b64 s[0:1], s[0:1], s[4:5]
	s_andn2_b64 vcc, exec, s[0:1]
	s_cbranch_vccnz .LBB0_405
	s_cmpk_lt_i32 s2, 0x440
	s_cselect_b64 s[4:5], -1, 0
	s_cmpk_gt_i32 s2, 0x43f
	v_readfirstlane_b32 s6, v1
	s_cbranch_scc1 .LBB0_366
	s_ashr_i32 s3, s2, 31
	s_lshr_b32 s3, s3, 29
	s_add_i32 s3, s2, s3
	s_ashr_i32 s7, s3, 3
	s_and_b32 s3, s3, -8
	s_sub_i32 s3, s2, s3
	s_cmp_lt_i32 s3, 0
	s_movk_i32 s8, 0x89
	s_cselect_b32 s8, s8, 0x88
	s_mul_i32 s3, s3, s8
	s_add_i32 s3, s3, s7
	s_ashr_i32 s7, s3, 31
	s_lshr_b32 s7, s7, 27
	s_add_i32 s7, s3, s7
	s_ashr_i32 s8, s7, 5
	s_andn2_b32 s7, s7, 31
	s_sub_i32 s3, s3, s7
	s_bfe_i32 s7, s3, 0x80000
	s_bfe_u32 s7, s7, 0x3000c
	s_add_i32 s7, s3, s7
	s_bfe_i32 s9, s7, 0x80000
	s_and_b32 s7, s7, 0xf8
	s_sub_i32 s3, s3, s7
	s_lshl_b32 s8, s8, 3
	s_sext_i32_i16 s9, s9
	s_sext_i32_i8 s3, s3
	s_add_i32 s33, s8, s3
	s_ashr_i32 s82, s9, 3

; __global__ void __launch_bounds__(512, 2) fwd_kernel(Args a) {
;     extern __shared__ __attribute__((aligned(16))) unsigned char lds[];
;     const int G = gridDim.x, tid = threadIdx.x, lane = tid & 63, wave = __builtin_amdgcn_readfirstlane(tid >> 6);
	.amdhsa_kernel _Z10fwd_kernel4Args
		.amdhsa_group_segment_fixed_size 0
		.amdhsa_private_segment_fixed_size 0
		.amdhsa_kernarg_size 480
		.amdhsa_user_sgpr_count 2
		.amdhsa_user_sgpr_dispatch_ptr 0
		.amdhsa_user_sgpr_queue_ptr 0
		.amdhsa_user_sgpr_kernarg_segment_ptr 1
		.amdhsa_user_sgpr_dispatch_id 0
		.amdhsa_user_sgpr_kernarg_preload_length 0
		.amdhsa_user_sgpr_kernarg_preload_offset 0
		.amdhsa_user_sgpr_private_segment_size 0
		.amdhsa_uses_dynamic_stack 0
		.amdhsa_enable_private_segment 0
		.amdhsa_system_sgpr_workgroup_id_x 1
		.amdhsa_system_sgpr_workgroup_id_y 0
		.amdhsa_system_sgpr_workgroup_id_z 0
		.amdhsa_system_sgpr_workgroup_info 0
		.amdhsa_system_vgpr_workitem_id 2
		.amdhsa_next_free_vgpr 256
		.amdhsa_next_free_sgpr 102
		.amdhsa_accum_offset 256
		.amdhsa_reserve_vcc 1
		.amdhsa_float_round_mode_32 0
		.amdhsa_float_round_mode_16_64 0
		.amdhsa_float_denorm_mode_32 3
		.amdhsa_float_denorm_mode_16_64 3
		.amdhsa_dx10_clamp 1
		.amdhsa_ieee_mode 1
		.amdhsa_fp16_overflow 0
		.amdhsa_tg_split 0
		.amdhsa_exception_fp_ieee_invalid_op 0
		.amdhsa_exception_fp_denorm_src 0
		.amdhsa_exception_fp_ieee_div_zero 0
		.amdhsa_exception_fp_ieee_overflow 0
		.amdhsa_exception_fp_ieee_underflow 0
		.amdhsa_exception_fp_ieee_inexact 0
		.amdhsa_exception_int_div_zero 0
	.end_amdhsa_kernel

; __global__ void __launch_bounds__(512, 2) fwd_kernel(Args a) {
;     extern __shared__ __attribute__((aligned(16))) unsigned char lds[];
;     const int G = gridDim.x, tid = threadIdx.x, lane = tid & 63, wave = __builtin_amdgcn_readfirstlane(tid >> 6);
amdhsa.kernels:
  - .agpr_count:     0
    .args:
      - .offset:         0
        .size:           224
        .value_kind:     by_value
      - .offset:         224
        .size:           4
        .value_kind:     hidden_block_count_x
      - .offset:         228
        .size:           4
        .value_kind:     hidden_block_count_y
      - .offset:         232
        .size:           4
        .value_kind:     hidden_block_count_z
      - .offset:         236
        .size:           2
        .value_kind:     hidden_group_size_x
      - .offset:         238
        .size:           2
        .value_kind:     hidden_group_size_y
      - .offset:         240
        .size:           2
        .value_kind:     hidden_group_size_z
      - .offset:         242
        .size:           2
        .value_kind:     hidden_remainder_x
      - .offset:         244
        .size:           2
        .value_kind:     hidden_remainder_y
      - .offset:         246
        .size:           2
        .value_kind:     hidden_remainder_z
      - .offset:         264
        .size:           8
        .value_kind:     hidden_global_offset_x
      - .offset:         272
        .size:           8
        .value_kind:     hidden_global_offset_y
      - .offset:         280
        .size:           8
        .value_kind:     hidden_global_offset_z
      - .offset:         288
        .size:           2
        .value_kind:     hidden_grid_dims
      - .offset:         312
        .size:           8
        .value_kind:     hidden_multigrid_sync_arg
      - .offset:         344
        .size:           4
        .value_kind:     hidden_dynamic_lds_size
    .group_segment_fixed_size: 0
    .kernarg_segment_align: 8
    .kernarg_segment_size: 480
    .language:       OpenCL C
    .language_version:
      - 2
      - 0
    .max_flat_workgroup_size: 512
    .name:           _Z10fwd_kernel4Args
    .private_segment_fixed_size: 0
    .sgpr_count:     108
    .sgpr_spill_count: 39
    .symbol:         _Z10fwd_kernel4Args.kd
    .uniform_work_group_size: 1
    .uses_dynamic_stack: false
    .vgpr_count:     256
    .vgpr_spill_count: 0
    .wavefront_size: 64
